# conversion split plus the six GEMM K-loop heads aligned to 64 bytes (code placement lever)
# baseline (speedup 1.0000x reference)
.LBB0_325:
	s_ashr_i32 s43, s42, 31
	s_lshl_b64 s[44:45], s[42:43], 20
	s_add_u32 s44, s24, s44
	s_addc_u32 s45, s25, s45
	s_and_b64 s[46:47], s[6:7], exec
	s_cselect_b32 s2, s45, s9
	s_cselect_b32 s11, s44, s8
	s_ashr_i32 s41, s40, 31
	s_lshl_b64 s[46:47], s[40:41], 20
	s_add_u32 s46, s26, s46
	s_addc_u32 s47, s27, s47
	s_and_b64 s[48:49], s[6:7], exec
	s_cselect_b32 s13, s47, s1
	s_cselect_b32 s41, s46, s0
	s_add_u32 s8, s8, 0x80080
	s_addc_u32 s9, s9, 0
	s_add_u32 s43, s0, 0x100
	v_mov_b32_e32 v10, 0
	s_addc_u32 s50, s1, 0
	s_mov_b32 s51, -2
	v_mov_b32_e32 v11, v10
	v_mov_b32_e32 v12, v10
	v_mov_b32_e32 v13, v10
	v_mov_b32_e32 v14, v10
	v_mov_b32_e32 v15, v10
	v_mov_b32_e32 v16, v10
	v_mov_b32_e32 v17, v10
	v_mov_b32_e32 v30, v10
	v_mov_b32_e32 v31, v10
	v_mov_b32_e32 v32, v10
	v_mov_b32_e32 v33, v10
	v_mov_b32_e32 v26, v10
	v_mov_b32_e32 v27, v10
	v_mov_b32_e32 v28, v10
	v_mov_b32_e32 v29, v10
	v_mov_b32_e32 v46, v10
	v_mov_b32_e32 v47, v10
	v_mov_b32_e32 v48, v10
	v_mov_b32_e32 v49, v10
	v_mov_b32_e32 v42, v10
	v_mov_b32_e32 v43, v10
	v_mov_b32_e32 v44, v10
	v_mov_b32_e32 v45, v10
	v_mov_b32_e32 v62, v10
	v_mov_b32_e32 v63, v10
	v_mov_b32_e32 v64, v10
	v_mov_b32_e32 v65, v10
	v_mov_b32_e32 v58, v10
	v_mov_b32_e32 v59, v10
	v_mov_b32_e32 v60, v10
	v_mov_b32_e32 v61, v10
	v_mov_b32_e32 v22, v10
	v_mov_b32_e32 v23, v10
	v_mov_b32_e32 v24, v10
	v_mov_b32_e32 v25, v10
	v_mov_b32_e32 v18, v10
	v_mov_b32_e32 v19, v10
	v_mov_b32_e32 v20, v10
	v_mov_b32_e32 v21, v10
	v_mov_b32_e32 v38, v10
	v_mov_b32_e32 v39, v10
	v_mov_b32_e32 v40, v10
	v_mov_b32_e32 v41, v10
	v_mov_b32_e32 v34, v10
	v_mov_b32_e32 v35, v10
	v_mov_b32_e32 v36, v10
	v_mov_b32_e32 v37, v10
	v_mov_b32_e32 v54, v10
	v_mov_b32_e32 v55, v10
	v_mov_b32_e32 v56, v10
	v_mov_b32_e32 v57, v10
	v_mov_b32_e32 v50, v10
	v_mov_b32_e32 v51, v10
	v_mov_b32_e32 v52, v10
	v_mov_b32_e32 v53, v10
	v_mov_b32_e32 v70, v10
	v_mov_b32_e32 v71, v10
	v_mov_b32_e32 v72, v10
	v_mov_b32_e32 v73, v10
	v_mov_b32_e32 v66, v10
	v_mov_b32_e32 v67, v10
	v_mov_b32_e32 v68, v10
	v_mov_b32_e32 v69, v10
	v_mov_b32_e32 v78, v10
	v_mov_b32_e32 v79, v10
	v_mov_b32_e32 v80, v10
	v_mov_b32_e32 v81, v10
	v_mov_b32_e32 v74, v10
	v_mov_b32_e32 v75, v10
	v_mov_b32_e32 v76, v10
	v_mov_b32_e32 v77, v10
	v_mov_b32_e32 v94, v10
	v_mov_b32_e32 v95, v10
	v_mov_b32_e32 v96, v10
	v_mov_b32_e32 v97, v10
	v_mov_b32_e32 v90, v10
	v_mov_b32_e32 v91, v10
	v_mov_b32_e32 v92, v10
	v_mov_b32_e32 v93, v10
	v_mov_b32_e32 v110, v10
	v_mov_b32_e32 v111, v10
	v_mov_b32_e32 v112, v10
	v_mov_b32_e32 v113, v10
	v_mov_b32_e32 v106, v10
	v_mov_b32_e32 v107, v10
	v_mov_b32_e32 v108, v10
	v_mov_b32_e32 v109, v10
	v_mov_b32_e32 v126, v10
	v_mov_b32_e32 v127, v10
	v_mov_b32_e32 v128, v10
	v_mov_b32_e32 v129, v10
	v_mov_b32_e32 v122, v10
	v_mov_b32_e32 v123, v10
	v_mov_b32_e32 v124, v10
	v_mov_b32_e32 v125, v10
	v_mov_b32_e32 v86, v10
	v_mov_b32_e32 v87, v10
	v_mov_b32_e32 v88, v10
	v_mov_b32_e32 v89, v10
	v_mov_b32_e32 v82, v10
	v_mov_b32_e32 v83, v10
	v_mov_b32_e32 v84, v10
	v_mov_b32_e32 v85, v10
	v_mov_b32_e32 v102, v10
	v_mov_b32_e32 v103, v10
	v_mov_b32_e32 v104, v10
	v_mov_b32_e32 v105, v10
	v_mov_b32_e32 v98, v10
	v_mov_b32_e32 v99, v10
	v_mov_b32_e32 v100, v10
	v_mov_b32_e32 v101, v10
	v_mov_b32_e32 v118, v10
	v_mov_b32_e32 v119, v10
	v_mov_b32_e32 v120, v10
	v_mov_b32_e32 v121, v10
	v_mov_b32_e32 v114, v10
	v_mov_b32_e32 v115, v10
	v_mov_b32_e32 v116, v10
	v_mov_b32_e32 v117, v10
	v_mov_b32_e32 v134, v10
	v_mov_b32_e32 v135, v10
	v_mov_b32_e32 v136, v10
	v_mov_b32_e32 v137, v10
	v_mov_b32_e32 v130, v10
	v_mov_b32_e32 v131, v10
	v_mov_b32_e32 v132, v10
	v_mov_b32_e32 v133, v10
	.p2alignl 6, 3212836864

.LBB0_721:
	s_add_u32 s28, s28, 0x18080
	s_addc_u32 s29, s29, 0
	s_add_u32 s2, s0, 0x100
	v_mov_b32_e32 v2, 0
	s_addc_u32 s13, s1, 0
	s_mov_b32 s56, -2
	v_mov_b32_e32 v3, v2
	v_mov_b32_e32 v4, v2
	v_mov_b32_e32 v5, v2
	v_mov_b32_e32 v6, v2
	v_mov_b32_e32 v7, v2
	v_mov_b32_e32 v8, v2
	v_mov_b32_e32 v9, v2
	v_mov_b32_e32 v18, v2
	v_mov_b32_e32 v19, v2
	v_mov_b32_e32 v20, v2
	v_mov_b32_e32 v21, v2
	v_mov_b32_e32 v22, v2
	v_mov_b32_e32 v23, v2
	v_mov_b32_e32 v24, v2
	v_mov_b32_e32 v25, v2
	v_mov_b32_e32 v34, v2
	v_mov_b32_e32 v35, v2
	v_mov_b32_e32 v36, v2
	v_mov_b32_e32 v37, v2
	v_mov_b32_e32 v38, v2
	v_mov_b32_e32 v39, v2
	v_mov_b32_e32 v40, v2
	v_mov_b32_e32 v41, v2
	v_mov_b32_e32 v50, v2
	v_mov_b32_e32 v51, v2
	v_mov_b32_e32 v52, v2
	v_mov_b32_e32 v53, v2
	v_mov_b32_e32 v54, v2
	v_mov_b32_e32 v55, v2
	v_mov_b32_e32 v56, v2
	v_mov_b32_e32 v57, v2
	v_mov_b32_e32 v10, v2
	v_mov_b32_e32 v11, v2
	v_mov_b32_e32 v12, v2
	v_mov_b32_e32 v13, v2
	v_mov_b32_e32 v14, v2
	v_mov_b32_e32 v15, v2
	v_mov_b32_e32 v16, v2
	v_mov_b32_e32 v17, v2
	v_mov_b32_e32 v26, v2
	v_mov_b32_e32 v27, v2
	v_mov_b32_e32 v28, v2
	v_mov_b32_e32 v29, v2
	v_mov_b32_e32 v30, v2
	v_mov_b32_e32 v31, v2
	v_mov_b32_e32 v32, v2
	v_mov_b32_e32 v33, v2
	v_mov_b32_e32 v42, v2
	v_mov_b32_e32 v43, v2
	v_mov_b32_e32 v44, v2
	v_mov_b32_e32 v45, v2
	v_mov_b32_e32 v46, v2
	v_mov_b32_e32 v47, v2
	v_mov_b32_e32 v48, v2
	v_mov_b32_e32 v49, v2
	v_mov_b32_e32 v58, v2
	v_mov_b32_e32 v59, v2
	v_mov_b32_e32 v60, v2
	v_mov_b32_e32 v61, v2
	v_mov_b32_e32 v62, v2
	v_mov_b32_e32 v63, v2
	v_mov_b32_e32 v64, v2
	v_mov_b32_e32 v65, v2
	v_mov_b32_e32 v66, v2
	v_mov_b32_e32 v67, v2
	v_mov_b32_e32 v68, v2
	v_mov_b32_e32 v69, v2
	v_mov_b32_e32 v70, v2
	v_mov_b32_e32 v71, v2
	v_mov_b32_e32 v72, v2
	v_mov_b32_e32 v73, v2
	v_mov_b32_e32 v82, v2
	v_mov_b32_e32 v83, v2
	v_mov_b32_e32 v84, v2
	v_mov_b32_e32 v85, v2
	v_mov_b32_e32 v86, v2
	v_mov_b32_e32 v87, v2
	v_mov_b32_e32 v88, v2
	v_mov_b32_e32 v89, v2
	v_mov_b32_e32 v98, v2
	v_mov_b32_e32 v99, v2
	v_mov_b32_e32 v100, v2
	v_mov_b32_e32 v101, v2
	v_mov_b32_e32 v102, v2
	v_mov_b32_e32 v103, v2
	v_mov_b32_e32 v104, v2
	v_mov_b32_e32 v105, v2
	v_mov_b32_e32 v114, v2
	v_mov_b32_e32 v115, v2
	v_mov_b32_e32 v116, v2
	v_mov_b32_e32 v117, v2
	v_mov_b32_e32 v118, v2
	v_mov_b32_e32 v119, v2
	v_mov_b32_e32 v120, v2
	v_mov_b32_e32 v121, v2
	v_mov_b32_e32 v74, v2
	v_mov_b32_e32 v75, v2
	v_mov_b32_e32 v76, v2
	v_mov_b32_e32 v77, v2
	v_mov_b32_e32 v78, v2
	v_mov_b32_e32 v79, v2
	v_mov_b32_e32 v80, v2
	v_mov_b32_e32 v81, v2
	v_mov_b32_e32 v90, v2
	v_mov_b32_e32 v91, v2
	v_mov_b32_e32 v92, v2
	v_mov_b32_e32 v93, v2
	v_mov_b32_e32 v94, v2
	v_mov_b32_e32 v95, v2
	v_mov_b32_e32 v96, v2
	v_mov_b32_e32 v97, v2
	v_mov_b32_e32 v106, v2
	v_mov_b32_e32 v107, v2
	v_mov_b32_e32 v108, v2
	v_mov_b32_e32 v109, v2
	v_mov_b32_e32 v110, v2
	v_mov_b32_e32 v111, v2
	v_mov_b32_e32 v112, v2
	v_mov_b32_e32 v113, v2
	v_mov_b32_e32 v122, v2
	v_mov_b32_e32 v123, v2
	v_mov_b32_e32 v124, v2
	v_mov_b32_e32 v125, v2
	v_mov_b32_e32 v126, v2
	v_mov_b32_e32 v127, v2
	v_mov_b32_e32 v128, v2
	v_mov_b32_e32 v129, v2
	.p2alignl 6, 3212836864

.LBB0_891:
	s_ashr_i32 s31, s30, 31
	s_lshl_b64 s[36:37], s[30:31], 18
	s_add_u32 s36, s3, s36
	s_addc_u32 s37, s20, s37
	s_and_b64 s[38:39], s[4:5], exec
	s_cselect_b32 s31, s37, s43
	s_cselect_b32 s53, s36, s42
	s_ashr_i32 s29, s28, 31
	s_lshl_b64 s[38:39], s[28:29], 18
	s_add_u32 s38, s21, s38
	s_addc_u32 s39, s23, s39
	s_and_b64 s[44:45], s[4:5], exec
	s_cselect_b32 s29, s39, s1
	s_cselect_b32 s54, s38, s0
	s_add_u32 s42, s42, 0x20080
	s_addc_u32 s43, s43, 0
	s_add_u32 s55, s0, 0x100
	v_mov_b32_e32 v34, 0
	s_addc_u32 s56, s1, 0
	s_mov_b32 s57, -2
	v_mov_b32_e32 v35, v34
	v_mov_b32_e32 v36, v34
	v_mov_b32_e32 v37, v34
	v_mov_b32_e32 v38, v34
	v_mov_b32_e32 v39, v34
	v_mov_b32_e32 v40, v34
	v_mov_b32_e32 v41, v34
	v_mov_b32_e32 v50, v34
	v_mov_b32_e32 v51, v34
	v_mov_b32_e32 v52, v34
	v_mov_b32_e32 v53, v34
	v_mov_b32_e32 v54, v34
	v_mov_b32_e32 v55, v34
	v_mov_b32_e32 v56, v34
	v_mov_b32_e32 v57, v34
	v_mov_b32_e32 v66, v34
	v_mov_b32_e32 v67, v34
	v_mov_b32_e32 v68, v34
	v_mov_b32_e32 v69, v34
	v_mov_b32_e32 v70, v34
	v_mov_b32_e32 v71, v34
	v_mov_b32_e32 v72, v34
	v_mov_b32_e32 v73, v34
	v_mov_b32_e32 v82, v34
	v_mov_b32_e32 v83, v34
	v_mov_b32_e32 v84, v34
	v_mov_b32_e32 v85, v34
	v_mov_b32_e32 v86, v34
	v_mov_b32_e32 v87, v34
	v_mov_b32_e32 v88, v34
	v_mov_b32_e32 v89, v34
	v_mov_b32_e32 v42, v34
	v_mov_b32_e32 v43, v34
	v_mov_b32_e32 v44, v34
	v_mov_b32_e32 v45, v34
	v_mov_b32_e32 v46, v34
	v_mov_b32_e32 v47, v34
	v_mov_b32_e32 v48, v34
	v_mov_b32_e32 v49, v34
	v_mov_b32_e32 v58, v34
	v_mov_b32_e32 v59, v34
	v_mov_b32_e32 v60, v34
	v_mov_b32_e32 v61, v34
	v_mov_b32_e32 v62, v34
	v_mov_b32_e32 v63, v34
	v_mov_b32_e32 v64, v34
	v_mov_b32_e32 v65, v34
	v_mov_b32_e32 v74, v34
	v_mov_b32_e32 v75, v34
	v_mov_b32_e32 v76, v34
	v_mov_b32_e32 v77, v34
	v_mov_b32_e32 v78, v34
	v_mov_b32_e32 v79, v34
	v_mov_b32_e32 v80, v34
	v_mov_b32_e32 v81, v34
	v_mov_b32_e32 v90, v34
	v_mov_b32_e32 v91, v34
	v_mov_b32_e32 v92, v34
	v_mov_b32_e32 v93, v34
	v_mov_b32_e32 v94, v34
	v_mov_b32_e32 v95, v34
	v_mov_b32_e32 v96, v34
	v_mov_b32_e32 v97, v34
	v_mov_b32_e32 v98, v34
	v_mov_b32_e32 v99, v34
	v_mov_b32_e32 v100, v34
	v_mov_b32_e32 v101, v34
	v_mov_b32_e32 v102, v34
	v_mov_b32_e32 v103, v34
	v_mov_b32_e32 v104, v34
	v_mov_b32_e32 v105, v34
	v_mov_b32_e32 v114, v34
	v_mov_b32_e32 v115, v34
	v_mov_b32_e32 v116, v34
	v_mov_b32_e32 v117, v34
	v_mov_b32_e32 v118, v34
	v_mov_b32_e32 v119, v34
	v_mov_b32_e32 v120, v34
	v_mov_b32_e32 v121, v34
	v_mov_b32_e32 v130, v34
	v_mov_b32_e32 v131, v34
	v_mov_b32_e32 v132, v34
	v_mov_b32_e32 v133, v34
	v_mov_b32_e32 v134, v34
	v_mov_b32_e32 v135, v34
	v_mov_b32_e32 v136, v34
	v_mov_b32_e32 v137, v34
	v_mov_b32_e32 v146, v34
	v_mov_b32_e32 v147, v34
	v_mov_b32_e32 v148, v34
	v_mov_b32_e32 v149, v34
	v_mov_b32_e32 v150, v34
	v_mov_b32_e32 v151, v34
	v_mov_b32_e32 v152, v34
	v_mov_b32_e32 v153, v34
	v_mov_b32_e32 v106, v34
	v_mov_b32_e32 v107, v34
	v_mov_b32_e32 v108, v34
	v_mov_b32_e32 v109, v34
	v_mov_b32_e32 v110, v34
	v_mov_b32_e32 v111, v34
	v_mov_b32_e32 v112, v34
	v_mov_b32_e32 v113, v34
	v_mov_b32_e32 v122, v34
	v_mov_b32_e32 v123, v34
	v_mov_b32_e32 v124, v34
	v_mov_b32_e32 v125, v34
	v_mov_b32_e32 v126, v34
	v_mov_b32_e32 v127, v34
	v_mov_b32_e32 v128, v34
	v_mov_b32_e32 v129, v34
	v_mov_b32_e32 v138, v34
	v_mov_b32_e32 v139, v34
	v_mov_b32_e32 v140, v34
	v_mov_b32_e32 v141, v34
	v_mov_b32_e32 v142, v34
	v_mov_b32_e32 v143, v34
	v_mov_b32_e32 v144, v34
	v_mov_b32_e32 v145, v34
	v_mov_b32_e32 v154, v34
	v_mov_b32_e32 v155, v34
	v_mov_b32_e32 v156, v34
	v_mov_b32_e32 v157, v34
	v_mov_b32_e32 v158, v34
	v_mov_b32_e32 v159, v34
	v_mov_b32_e32 v160, v34
	v_mov_b32_e32 v161, v34
	.p2alignl 6, 3212836864

.LBB0_966:
	s_ashr_i32 s51, s50, 31
	s_lshl_b64 s[52:53], s[50:51], 19
	s_add_u32 s52, s20, s52
	s_addc_u32 s53, s21, s53
	s_and_b64 s[54:55], s[6:7], exec
	s_cselect_b32 s51, s53, s59
	s_cselect_b32 s57, s52, s58
	s_ashr_i32 s49, s48, 31
	s_lshl_b64 s[54:55], s[48:49], 19
	s_add_u32 s54, s24, s54
	s_addc_u32 s55, s25, s55
	s_and_b64 s[60:61], s[6:7], exec
	s_cselect_b32 s49, s55, s1
	s_cselect_b32 s74, s54, s0
	s_add_u32 s58, s58, 0x40080
	s_addc_u32 s59, s59, 0
	s_add_u32 s75, s0, 0x100
	v_mov_b32_e32 v34, 0
	s_addc_u32 s76, s1, 0
	s_mov_b32 s77, -2
	v_mov_b32_e32 v35, v34
	v_mov_b32_e32 v36, v34
	v_mov_b32_e32 v37, v34
	v_mov_b32_e32 v38, v34
	v_mov_b32_e32 v39, v34
	v_mov_b32_e32 v40, v34
	v_mov_b32_e32 v41, v34
	v_mov_b32_e32 v50, v34
	v_mov_b32_e32 v51, v34
	v_mov_b32_e32 v52, v34
	v_mov_b32_e32 v53, v34
	v_mov_b32_e32 v54, v34
	v_mov_b32_e32 v55, v34
	v_mov_b32_e32 v56, v34
	v_mov_b32_e32 v57, v34
	v_mov_b32_e32 v66, v34
	v_mov_b32_e32 v67, v34
	v_mov_b32_e32 v68, v34
	v_mov_b32_e32 v69, v34
	v_mov_b32_e32 v70, v34
	v_mov_b32_e32 v71, v34
	v_mov_b32_e32 v72, v34
	v_mov_b32_e32 v73, v34
	v_mov_b32_e32 v82, v34
	v_mov_b32_e32 v83, v34
	v_mov_b32_e32 v84, v34
	v_mov_b32_e32 v85, v34
	v_mov_b32_e32 v86, v34
	v_mov_b32_e32 v87, v34
	v_mov_b32_e32 v88, v34
	v_mov_b32_e32 v89, v34
	v_mov_b32_e32 v42, v34
	v_mov_b32_e32 v43, v34
	v_mov_b32_e32 v44, v34
	v_mov_b32_e32 v45, v34
	v_mov_b32_e32 v46, v34
	v_mov_b32_e32 v47, v34
	v_mov_b32_e32 v48, v34
	v_mov_b32_e32 v49, v34
	v_mov_b32_e32 v58, v34
	v_mov_b32_e32 v59, v34
	v_mov_b32_e32 v60, v34
	v_mov_b32_e32 v61, v34
	v_mov_b32_e32 v62, v34
	v_mov_b32_e32 v63, v34
	v_mov_b32_e32 v64, v34
	v_mov_b32_e32 v65, v34
	v_mov_b32_e32 v74, v34
	v_mov_b32_e32 v75, v34
	v_mov_b32_e32 v76, v34
	v_mov_b32_e32 v77, v34
	v_mov_b32_e32 v78, v34
	v_mov_b32_e32 v79, v34
	v_mov_b32_e32 v80, v34
	v_mov_b32_e32 v81, v34
	v_mov_b32_e32 v90, v34
	v_mov_b32_e32 v91, v34
	v_mov_b32_e32 v92, v34
	v_mov_b32_e32 v93, v34
	v_mov_b32_e32 v94, v34
	v_mov_b32_e32 v95, v34
	v_mov_b32_e32 v96, v34
	v_mov_b32_e32 v97, v34
	v_mov_b32_e32 v98, v34
	v_mov_b32_e32 v99, v34
	v_mov_b32_e32 v100, v34
	v_mov_b32_e32 v101, v34
	v_mov_b32_e32 v102, v34
	v_mov_b32_e32 v103, v34
	v_mov_b32_e32 v104, v34
	v_mov_b32_e32 v105, v34
	v_mov_b32_e32 v114, v34
	v_mov_b32_e32 v115, v34
	v_mov_b32_e32 v116, v34
	v_mov_b32_e32 v117, v34
	v_mov_b32_e32 v118, v34
	v_mov_b32_e32 v119, v34
	v_mov_b32_e32 v120, v34
	v_mov_b32_e32 v121, v34
	v_mov_b32_e32 v130, v34
	v_mov_b32_e32 v131, v34
	v_mov_b32_e32 v132, v34
	v_mov_b32_e32 v133, v34
	v_mov_b32_e32 v134, v34
	v_mov_b32_e32 v135, v34
	v_mov_b32_e32 v136, v34
	v_mov_b32_e32 v137, v34
	v_mov_b32_e32 v146, v34
	v_mov_b32_e32 v147, v34
	v_mov_b32_e32 v148, v34
	v_mov_b32_e32 v149, v34
	v_mov_b32_e32 v150, v34
	v_mov_b32_e32 v151, v34
	v_mov_b32_e32 v152, v34
	v_mov_b32_e32 v153, v34
	v_mov_b32_e32 v106, v34
	v_mov_b32_e32 v107, v34
	v_mov_b32_e32 v108, v34
	v_mov_b32_e32 v109, v34
	v_mov_b32_e32 v110, v34
	v_mov_b32_e32 v111, v34
	v_mov_b32_e32 v112, v34
	v_mov_b32_e32 v113, v34
	v_mov_b32_e32 v122, v34
	v_mov_b32_e32 v123, v34
	v_mov_b32_e32 v124, v34
	v_mov_b32_e32 v125, v34
	v_mov_b32_e32 v126, v34
	v_mov_b32_e32 v127, v34
	v_mov_b32_e32 v128, v34
	v_mov_b32_e32 v129, v34
	v_mov_b32_e32 v138, v34
	v_mov_b32_e32 v139, v34
	v_mov_b32_e32 v140, v34
	v_mov_b32_e32 v141, v34
	v_mov_b32_e32 v142, v34
	v_mov_b32_e32 v143, v34
	v_mov_b32_e32 v144, v34
	v_mov_b32_e32 v145, v34
	v_mov_b32_e32 v154, v34
	v_mov_b32_e32 v155, v34
	v_mov_b32_e32 v156, v34
	v_mov_b32_e32 v157, v34
	v_mov_b32_e32 v158, v34
	v_mov_b32_e32 v159, v34
	v_mov_b32_e32 v160, v34
	v_mov_b32_e32 v161, v34
	.p2alignl 6, 3212836864

.LBB0_1071:
	s_ashr_i32 s23, s22, 31
	s_lshl_b64 s[28:29], s[22:23], 19
	s_add_u32 s28, s2, s28
	s_addc_u32 s29, s3, s29
	s_and_b64 s[30:31], s[4:5], exec
	s_cselect_b32 s23, s29, s37
	s_cselect_b32 s48, s28, s36
	s_ashr_i32 s19, s18, 31
	s_lshl_b64 s[30:31], s[18:19], 19
	s_add_u32 s30, s17, s30
	s_addc_u32 s31, s20, s31
	s_and_b64 s[38:39], s[4:5], exec
	s_cselect_b32 s19, s31, s1
	s_cselect_b32 s49, s30, s0
	s_add_u32 s36, s36, 0x40080
	s_addc_u32 s37, s37, 0
	s_add_u32 s50, s0, 0x100
	v_mov_b32_e32 v34, 0
	s_addc_u32 s51, s1, 0
	s_mov_b32 s52, -2
	v_mov_b32_e32 v35, v34
	v_mov_b32_e32 v36, v34
	v_mov_b32_e32 v37, v34
	v_mov_b32_e32 v38, v34
	v_mov_b32_e32 v39, v34
	v_mov_b32_e32 v40, v34
	v_mov_b32_e32 v41, v34
	v_mov_b32_e32 v50, v34
	v_mov_b32_e32 v51, v34
	v_mov_b32_e32 v52, v34
	v_mov_b32_e32 v53, v34
	v_mov_b32_e32 v54, v34
	v_mov_b32_e32 v55, v34
	v_mov_b32_e32 v56, v34
	v_mov_b32_e32 v57, v34
	v_mov_b32_e32 v66, v34
	v_mov_b32_e32 v67, v34
	v_mov_b32_e32 v68, v34
	v_mov_b32_e32 v69, v34
	v_mov_b32_e32 v70, v34
	v_mov_b32_e32 v71, v34
	v_mov_b32_e32 v72, v34
	v_mov_b32_e32 v73, v34
	v_mov_b32_e32 v82, v34
	v_mov_b32_e32 v83, v34
	v_mov_b32_e32 v84, v34
	v_mov_b32_e32 v85, v34
	v_mov_b32_e32 v86, v34
	v_mov_b32_e32 v87, v34
	v_mov_b32_e32 v88, v34
	v_mov_b32_e32 v89, v34
	v_mov_b32_e32 v42, v34
	v_mov_b32_e32 v43, v34
	v_mov_b32_e32 v44, v34
	v_mov_b32_e32 v45, v34
	v_mov_b32_e32 v46, v34
	v_mov_b32_e32 v47, v34
	v_mov_b32_e32 v48, v34
	v_mov_b32_e32 v49, v34
	v_mov_b32_e32 v58, v34
	v_mov_b32_e32 v59, v34
	v_mov_b32_e32 v60, v34
	v_mov_b32_e32 v61, v34
	v_mov_b32_e32 v62, v34
	v_mov_b32_e32 v63, v34
	v_mov_b32_e32 v64, v34
	v_mov_b32_e32 v65, v34
	v_mov_b32_e32 v74, v34
	v_mov_b32_e32 v75, v34
	v_mov_b32_e32 v76, v34
	v_mov_b32_e32 v77, v34
	v_mov_b32_e32 v78, v34
	v_mov_b32_e32 v79, v34
	v_mov_b32_e32 v80, v34
	v_mov_b32_e32 v81, v34
	v_mov_b32_e32 v90, v34
	v_mov_b32_e32 v91, v34
	v_mov_b32_e32 v92, v34
	v_mov_b32_e32 v93, v34
	v_mov_b32_e32 v94, v34
	v_mov_b32_e32 v95, v34
	v_mov_b32_e32 v96, v34
	v_mov_b32_e32 v97, v34
	v_mov_b32_e32 v98, v34
	v_mov_b32_e32 v99, v34
	v_mov_b32_e32 v100, v34
	v_mov_b32_e32 v101, v34
	v_mov_b32_e32 v102, v34
	v_mov_b32_e32 v103, v34
	v_mov_b32_e32 v104, v34
	v_mov_b32_e32 v105, v34
	v_mov_b32_e32 v114, v34
	v_mov_b32_e32 v115, v34
	v_mov_b32_e32 v116, v34
	v_mov_b32_e32 v117, v34
	v_mov_b32_e32 v118, v34
	v_mov_b32_e32 v119, v34
	v_mov_b32_e32 v120, v34
	v_mov_b32_e32 v121, v34
	v_mov_b32_e32 v130, v34
	v_mov_b32_e32 v131, v34
	v_mov_b32_e32 v132, v34
	v_mov_b32_e32 v133, v34
	v_mov_b32_e32 v134, v34
	v_mov_b32_e32 v135, v34
	v_mov_b32_e32 v136, v34
	v_mov_b32_e32 v137, v34
	v_mov_b32_e32 v146, v34
	v_mov_b32_e32 v147, v34
	v_mov_b32_e32 v148, v34
	v_mov_b32_e32 v149, v34
	v_mov_b32_e32 v150, v34
	v_mov_b32_e32 v151, v34
	v_mov_b32_e32 v152, v34
	v_mov_b32_e32 v153, v34
	v_mov_b32_e32 v106, v34
	v_mov_b32_e32 v107, v34
	v_mov_b32_e32 v108, v34
	v_mov_b32_e32 v109, v34
	v_mov_b32_e32 v110, v34
	v_mov_b32_e32 v111, v34
	v_mov_b32_e32 v112, v34
	v_mov_b32_e32 v113, v34
	v_mov_b32_e32 v122, v34
	v_mov_b32_e32 v123, v34
	v_mov_b32_e32 v124, v34
	v_mov_b32_e32 v125, v34
	v_mov_b32_e32 v126, v34
	v_mov_b32_e32 v127, v34
	v_mov_b32_e32 v128, v34
	v_mov_b32_e32 v129, v34
	v_mov_b32_e32 v138, v34
	v_mov_b32_e32 v139, v34
	v_mov_b32_e32 v140, v34
	v_mov_b32_e32 v141, v34
	v_mov_b32_e32 v142, v34
	v_mov_b32_e32 v143, v34
	v_mov_b32_e32 v144, v34
	v_mov_b32_e32 v145, v34
	v_mov_b32_e32 v154, v34
	v_mov_b32_e32 v155, v34
	v_mov_b32_e32 v156, v34
	v_mov_b32_e32 v157, v34
	v_mov_b32_e32 v158, v34
	v_mov_b32_e32 v159, v34
	v_mov_b32_e32 v160, v34
	v_mov_b32_e32 v161, v34
	.p2alignl 6, 3212836864

.LBB0_1157:
	s_ashr_i32 s55, s54, 31
	s_lshl_b64 s[12:13], s[54:55], 21
	s_add_u32 s5, s25, s12
	s_addc_u32 s7, s33, s13
	s_ashr_i32 s51, s50, 31
	s_lshl_b64 s[12:13], s[50:51], 7
	s_add_u32 s58, s5, s12
	s_addc_u32 s59, s7, s13
	s_ashr_i32 s53, s52, 31
	s_lshl_b64 s[14:15], s[52:53], 21
	s_add_u32 s5, s34, s14
	s_addc_u32 s7, s35, s15
	s_add_u32 s60, s5, s12
	s_addc_u32 s61, s7, s13
	s_cmp_lt_i32 s17, 1
	s_cbranch_scc1 .LBB0_1166
	s_and_b64 s[12:13], s[56:57], exec
	s_cselect_b32 s5, s59, s11
	s_cselect_b32 s7, s58, s10
	s_cselect_b32 s9, s61, s1
	s_cselect_b32 s14, s60, s0
	s_add_i32 s15, s17, -2
	s_add_u32 s10, s10, 0x100080
	s_addc_u32 s11, s11, 0
	s_add_u32 s18, s0, 0x100
	v_mov_b32_e32 v34, 0
	s_addc_u32 s19, s1, 0
	s_mov_b32 s0, 0
	v_mov_b32_e32 v35, v34
	v_mov_b32_e32 v36, v34
	v_mov_b32_e32 v37, v34
	v_mov_b32_e32 v38, v34
	v_mov_b32_e32 v39, v34
	v_mov_b32_e32 v40, v34
	v_mov_b32_e32 v41, v34
	v_mov_b32_e32 v50, v34
	v_mov_b32_e32 v51, v34
	v_mov_b32_e32 v52, v34
	v_mov_b32_e32 v53, v34
	v_mov_b32_e32 v54, v34
	v_mov_b32_e32 v55, v34
	v_mov_b32_e32 v56, v34
	v_mov_b32_e32 v57, v34
	v_mov_b32_e32 v66, v34
	v_mov_b32_e32 v67, v34
	s_waitcnt vmcnt(0)
	v_mov_b32_e32 v68, v34
	v_mov_b32_e32 v69, v34
	v_mov_b32_e32 v70, v34
	v_mov_b32_e32 v71, v34
	v_mov_b32_e32 v72, v34
	v_mov_b32_e32 v73, v34
	v_mov_b32_e32 v82, v34
	v_mov_b32_e32 v83, v34
	v_mov_b32_e32 v84, v34
	v_mov_b32_e32 v85, v34
	v_mov_b32_e32 v86, v34
	v_mov_b32_e32 v87, v34
	v_mov_b32_e32 v88, v34
	v_mov_b32_e32 v89, v34
	v_mov_b32_e32 v42, v34
	v_mov_b32_e32 v43, v34
	v_mov_b32_e32 v44, v34
	v_mov_b32_e32 v45, v34
	v_mov_b32_e32 v46, v34
	v_mov_b32_e32 v47, v34
	v_mov_b32_e32 v48, v34
	v_mov_b32_e32 v49, v34
	v_mov_b32_e32 v58, v34
	v_mov_b32_e32 v59, v34
	v_mov_b32_e32 v60, v34
	v_mov_b32_e32 v61, v34
	v_mov_b32_e32 v62, v34
	v_mov_b32_e32 v63, v34
	v_mov_b32_e32 v64, v34
	v_mov_b32_e32 v65, v34
	v_mov_b32_e32 v74, v34
	v_mov_b32_e32 v75, v34
	v_mov_b32_e32 v76, v34
	v_mov_b32_e32 v77, v34
	v_mov_b32_e32 v78, v34
	v_mov_b32_e32 v79, v34
	v_mov_b32_e32 v80, v34
	v_mov_b32_e32 v81, v34
	v_mov_b32_e32 v90, v34
	v_mov_b32_e32 v91, v34
	v_mov_b32_e32 v92, v34
	v_mov_b32_e32 v93, v34
	v_mov_b32_e32 v94, v34
	v_mov_b32_e32 v95, v34
	v_mov_b32_e32 v96, v34
	v_mov_b32_e32 v97, v34
	v_mov_b32_e32 v98, v34
	v_mov_b32_e32 v99, v34
	v_mov_b32_e32 v100, v34
	v_mov_b32_e32 v101, v34
	v_mov_b32_e32 v102, v34
	v_mov_b32_e32 v103, v34
	v_mov_b32_e32 v104, v34
	v_mov_b32_e32 v105, v34
	v_mov_b32_e32 v114, v34
	v_mov_b32_e32 v115, v34
	v_mov_b32_e32 v116, v34
	v_mov_b32_e32 v117, v34
	v_mov_b32_e32 v118, v34
	v_mov_b32_e32 v119, v34
	v_mov_b32_e32 v120, v34
	v_mov_b32_e32 v121, v34
	v_mov_b32_e32 v130, v34
	v_mov_b32_e32 v131, v34
	v_mov_b32_e32 v132, v34
	v_mov_b32_e32 v133, v34
	v_mov_b32_e32 v134, v34
	v_mov_b32_e32 v135, v34
	v_mov_b32_e32 v136, v34
	v_mov_b32_e32 v137, v34
	v_mov_b32_e32 v146, v34
	v_mov_b32_e32 v147, v34
	v_mov_b32_e32 v148, v34
	v_mov_b32_e32 v149, v34
	v_mov_b32_e32 v150, v34
	v_mov_b32_e32 v151, v34
	v_mov_b32_e32 v152, v34
	v_mov_b32_e32 v153, v34
	v_mov_b32_e32 v106, v34
	v_mov_b32_e32 v107, v34
	v_mov_b32_e32 v108, v34
	v_mov_b32_e32 v109, v34
	v_mov_b32_e32 v110, v34
	v_mov_b32_e32 v111, v34
	v_mov_b32_e32 v112, v34
	v_mov_b32_e32 v113, v34
	v_mov_b32_e32 v122, v34
	v_mov_b32_e32 v123, v34
	v_mov_b32_e32 v124, v34
	v_mov_b32_e32 v125, v34
	v_mov_b32_e32 v126, v34
	v_mov_b32_e32 v127, v34
	v_mov_b32_e32 v128, v34
	v_mov_b32_e32 v129, v34
	v_mov_b32_e32 v138, v34
	v_mov_b32_e32 v139, v34
	v_mov_b32_e32 v140, v34
	v_mov_b32_e32 v141, v34
	v_mov_b32_e32 v142, v34
	v_mov_b32_e32 v143, v34
	v_mov_b32_e32 v144, v34
	v_mov_b32_e32 v145, v34
	v_mov_b32_e32 v154, v34
	v_mov_b32_e32 v155, v34
	v_mov_b32_e32 v156, v34
	v_mov_b32_e32 v157, v34
	v_mov_b32_e32 v158, v34
	v_mov_b32_e32 v159, v34
	v_mov_b32_e32 v160, v34
	v_mov_b32_e32 v161, v34
	.p2alignl 6, 3212836864
